# prologues: diff2 K(1)/V(0) loads issued before the K(0) wait; dilated item bias-table load joins the Q/first-tile round trip
# speedup vs baseline: 1.0284x; 1.0025x over previous
; #define LAS __attribute__((address_space(3)))
; #define DL_LOAD(j0_) do { if ((j0_) >= 0 && (j0_) < L) { _Pragma("unroll") for (int i = 0; i < 4; ++i) { const bf16* sp = sKb + (size_t)((j0_) + rowK + 16 * i) * dil * 1536; gk[i] = *(const v4u*)sp; gv[i] = *(const v4u*)(sp + (size_t)T * (OFF_LV - OFF_LK)); } } } while (0)
; __device__ __forceinline__ void dil_item(const Params& p, LAS unsigned char* lds, const int bitem) {
;     ...
;     const int jq0 = 128 * ii + 32 * wq, jq = jq0 + r;
;     const size_t tq = (size_t)b * 2048 + (size_t)jq * dil + cls;
;     __syncthreads();
;     if (ht < 129) tab[ht] = gtab[ht];
;     v8s Q[1][8];
; #pragma unroll
;     for (int ks = 0; ks < 8; ++ks) Q[0][ks] = *(const v8s*)(Z + (size_t)T * OFF_LQ + tq * 1536 + g * 512 + hh * 128 + ks * 16 + h * 8);
;     AttnAcc<1> st; attn_init<1>(st);
;     const int rowK = ht >> 4, ccK = ht & 15;
;     const bf16* sKb = Z + (size_t)T * OFF_LK + ((size_t)b * 2048 + cls) * 1536 + g * 512 + hh * 128 + ccK * 8;
;     LAS unsigned char* dK = base + DL_K + rowK * 272 + ccK * 16; LAS unsigned char* dV = base + DL_VT + rowK * 320 + ccK * 16;
;     const int jbase = 128 * ii - 64;
;     const float c1 = 0.08838834764831845f * LOG2E;
;     v4u gk[4], gv[4];
;     ...
;     DL_LOAD(jbase);
.LBB0_158:
	v_mov_b32_e32 v2, v204
	s_lshl_b32 s6, s50, 1
	s_addk_i32 s6, 0xfe00
	v_ashrrev_i32_e32 v3, 8, v2
	v_add_u32_e32 v7, s6, v3
	v_readlane_b32 s6, v250, 10
	v_ashrrev_i32_e32 v146, 9, v7
	v_bfe_u32 v173, v7, 4, 2
	v_mov_b32_e32 v0, s6
	s_movk_i32 s6, 0x210
	v_lshlrev_b32_e32 v147, 10, v3
	v_add_u32_e32 v147, 0x12d20, v147
	s_movk_i32 s6, 0x81
	v_and_b32_e32 v0, 0xff, v2
	v_subrev_u32_e32 v0, 64, v0
	v_cmp_gt_u32_e64 s[10:11], s6, v0
	v_mov_b32_e32 v252, 0xf149f2ca
	s_barrier
	s_and_saveexec_b64 s[6:7], s[10:11]
	s_cbranch_execz .LBB0_160
	v_lshl_or_b32 v0, v146, 2, v173
	s_movk_i32 s10, 0x84
	v_mul_lo_u32 v4, v0, s10
	v_readlane_b32 s10, v249, 30
	v_ashrrev_i32_e32 v5, 31, v4
	v_readlane_b32 s11, v249, 31
	v_and_b32_e32 v0, 0xff, v2
	v_subrev_u32_e32 v0, 64, v0
	v_lshlrev_b32_e32 v0, 2, v0
	s_nop 0
	v_lshl_add_u64 v[4:5], v[4:5], 2, s[10:11]
	v_lshl_add_u64 v[4:5], v[4:5], 0, v[0:1]
	global_load_dword v252, v[4:5], off
.LBB0_160:
	s_or_b64 exec, exec, s[6:7]
	v_and_b32_e32 v253, 0xff, v2
	v_lshl_add_u32 v253, v253, 2, v147
	v_add_u32_e32 v253, 0xffffff00, v253
	v_lshlrev_b32_e32 v180, 1, v146
	v_lshrrev_b32_e64 v5, v180, 16
	v_add_u32_e32 v5, -1, v5
	s_movk_i32 s6, 0x1ff
	v_ashrrev_i32_e32 v182, 6, v2
	v_and_b32_e32 v0, 0x1ff, v7
	v_bitop3_b32 v16, v5, v7, s6 bitop3:0x80
	v_sub_u32_e32 v5, 4, v180
	v_lshrrev_b32_e32 v10, v5, v0
	v_lshlrev_b32_e32 v0, 5, v182
	v_lshlrev_b32_e32 v152, 7, v16
	v_and_b32_e32 v5, 0x60, v0
	v_and_b32_e32 v4, 31, v2
	v_or_b32_e32 v181, v152, v5
	v_lshlrev_b32_e32 v8, 5, v7
	v_lshlrev_b32_e64 v11, v180, -1
	v_or_b32_e32 v0, v181, v4
	v_and_b32_e32 v12, 0x3800, v8
	v_readlane_b32 s6, v249, 32
	v_lshlrev_b64 v[8:9], v180, v[0:1]
	v_bitop3_b32 v0, v10, v12, v11 bitop3:0xdc
	v_readlane_b32 s7, v249, 33
	v_lshl_add_u64 v[148:149], v[8:9], 0, v[0:1]
	v_bfe_u32 v6, v2, 5, 1
	v_mov_b64_e32 v[8:9], s[6:7]
	v_mad_u64_u32 v[8:9], s[6:7], v148, s24, v[8:9]
	v_mov_b32_e32 v10, v9
	v_mad_u64_u32 v[10:11], s[6:7], v149, s24, v[10:11]
	v_mov_b32_e32 v9, v10
	v_and_b32_e32 v10, 0xfffffe00, v7
	v_ashrrev_i32_e32 v11, 31, v10
	v_lshlrev_b64 v[10:11], 1, v[10:11]
	v_lshl_add_u64 v[8:9], v[8:9], 0, v[10:11]
	v_lshlrev_b32_e32 v12, 8, v173
	v_mov_b32_e32 v13, v1
	v_lshl_add_u64 v[8:9], v[8:9], 0, v[12:13]
	v_lshlrev_b32_e32 v14, 4, v6
	v_mov_b32_e32 v15, v1
	v_lshl_add_u64 v[8:9], v[8:9], 0, v[14:15]
	global_load_dwordx4 v[82:85], v[8:9], off
	global_load_dwordx4 v[86:89], v[8:9], off offset:32
	global_load_dwordx4 v[90:93], v[8:9], off offset:64
	global_load_dwordx4 v[94:97], v[8:9], off offset:96
	global_load_dwordx4 v[98:101], v[8:9], off offset:128
	global_load_dwordx4 v[102:105], v[8:9], off offset:160
	global_load_dwordx4 v[106:109], v[8:9], off offset:192
	global_load_dwordx4 v[110:113], v[8:9], off offset:224
	s_movk_i32 s6, 0x800
	v_lshrrev_b32_e64 v185, v180, s6
	v_readlane_b32 s6, v249, 34
	v_readlane_b32 s7, v249, 35
	v_and_b32_e32 v8, 15, v2
	v_subrev_u32_e32 v9, 64, v152
	v_mov_b64_e32 v[14:15], s[6:7]
	v_mad_u64_u32 v[14:15], s[6:7], v0, s24, v[14:15]
	v_lshl_add_u64 v[10:11], v[14:15], 0, v[10:11]
	v_lshl_add_u64 v[10:11], v[10:11], 0, v[12:13]
	v_lshlrev_b32_e32 v150, 4, v8
	v_mov_b32_e32 v151, v1
	v_cmp_ne_u32_e32 vcc, 0, v16
	v_cmp_lt_i32_e64 s[38:39], v9, v185
	v_lshrrev_b32_sdwa v7, v211, v2 dst_sel:DWORD dst_unused:UNUSED_PAD src0_sel:DWORD src1_sel:BYTE_0
	v_lshl_add_u64 v[154:155], v[10:11], 0, v[150:151]
	s_and_b64 s[10:11], vcc, s[38:39]
	s_and_saveexec_b64 s[6:7], s[10:11]
	s_cbranch_execz .LBB0_162
	v_or_b32_e32 v10, v9, v7
	v_ashrrev_i32_e32 v11, 31, v10
	v_lshlrev_b64 v[12:13], v180, v[10:11]
	v_mad_u64_u32 v[14:15], s[10:11], v12, s24, v[154:155]
	v_mov_b32_e32 v12, v15
	v_mad_u64_u32 v[12:13], s[10:11], v13, s24, v[12:13]
	v_add_co_u32_e32 v16, vcc, s25, v14
	v_mov_b32_e32 v15, v12
	s_nop 0
	v_addc_co_u32_e32 v17, vcc, 0, v12, vcc
	v_or_b32_e32 v12, 16, v10
	v_ashrrev_i32_e32 v13, 31, v12
	v_lshlrev_b64 v[12:13], v180, v[12:13]
	v_mad_u64_u32 v[18:19], s[10:11], v12, s24, v[154:155]
	v_mov_b32_e32 v12, v19
	v_mad_u64_u32 v[12:13], s[10:11], v13, s24, v[12:13]
	v_mov_b32_e32 v19, v12
	global_load_dwordx4 v[114:117], v[14:15], off
	global_load_dwordx4 v[118:121], v[18:19], off
	v_add_co_u32_e32 v14, vcc, s25, v18
	s_nop 1
	v_addc_co_u32_e32 v15, vcc, 0, v12, vcc
	v_or_b32_e32 v12, 32, v10
	v_ashrrev_i32_e32 v13, 31, v12
	v_lshlrev_b64 v[12:13], v180, v[12:13]
	global_load_dwordx4 v[122:125], v[16:17], off
	global_load_dwordx4 v[126:129], v[14:15], off
	v_mad_u64_u32 v[14:15], s[10:11], v12, s24, v[154:155]
	v_or_b32_e32 v10, 48, v10
	v_mov_b32_e32 v12, v15
	v_ashrrev_i32_e32 v11, 31, v10
	v_mad_u64_u32 v[12:13], s[10:11], v13, s24, v[12:13]
	v_add_co_u32_e32 v16, vcc, s25, v14
	v_lshlrev_b64 v[10:11], v180, v[10:11]
	v_mov_b32_e32 v15, v12
	v_addc_co_u32_e32 v17, vcc, 0, v12, vcc
	v_mad_u64_u32 v[12:13], s[10:11], v10, s24, v[154:155]
	v_mov_b32_e32 v10, v13
	v_mad_u64_u32 v[10:11], s[10:11], v11, s24, v[10:11]
	v_mov_b32_e32 v13, v10
	global_load_dwordx4 v[130:133], v[14:15], off
	global_load_dwordx4 v[134:137], v[12:13], off
	v_add_co_u32_e32 v12, vcc, 0x3000000, v12
	s_nop 1
	v_addc_co_u32_e32 v13, vcc, 0, v10, vcc
	global_load_dwordx4 v[138:141], v[16:17], off
	global_load_dwordx4 v[142:145], v[12:13], off
; #define LAS __attribute__((address_space(3)))
; #define DL_LOAD(j0_) do { if ((j0_) >= 0 && (j0_) < L) { _Pragma("unroll") for (int i = 0; i < 4; ++i) { const bf16* sp = sKb + (size_t)((j0_) + rowK + 16 * i) * dil * 1536; gk[i] = *(const v4u*)sp; gv[i] = *(const v4u*)(sp + (size_t)T * (OFF_LV - OFF_LK)); } } } while (0)
; template <int NM> __device__ __forceinline__ void attn_init(AttnAcc<NM>& st) {
; #pragma unroll
;     for (int m = 0; m < NM; ++m) { st.m[m] = NEGBIG; st.l[m] = 0.f;
; #pragma unroll
;         for (int eb = 0; eb < 4; ++eb)
; #pragma unroll
;             for (int i = 0; i < 16; ++i) st.O[m][eb][i] = 0.f; }
; }
; __device__ __forceinline__ void dil_item(const Params& p, LAS unsigned char* lds, const int bitem) {
;     ...
;     if (ht < 129) tab[ht] = gtab[ht];
;     v8s Q[1][8];
; #pragma unroll
;     for (int ks = 0; ks < 8; ++ks) Q[0][ks] = *(const v8s*)(Z + (size_t)T * OFF_LQ + tq * 1536 + g * 512 + hh * 128 + ks * 16 + h * 8);
;     AttnAcc<1> st; attn_init<1>(st);
;     const int rowK = ht >> 4, ccK = ht & 15;
;     const bf16* sKb = Z + (size_t)T * OFF_LK + ((size_t)b * 2048 + cls) * 1536 + g * 512 + hh * 128 + ccK * 8;
;     LAS unsigned char* dK = base + DL_K + rowK * 272 + ccK * 16; LAS unsigned char* dV = base + DL_VT + rowK * 320 + ccK * 16;
;     const int jbase = 128 * ii - 64;
;     const float c1 = 0.08838834764831845f * LOG2E;
;     v4u gk[4], gv[4];
;     ...
;     DL_LOAD(jbase);
.LBB0_162:
	s_or_b64 exec, exec, s[6:7]
	v_mul_i32_i24_e32 v3, 0x9400, v3
	v_add_u32_e32 v3, 0, v3
	v_and_b32_e32 v151, 63, v2
	v_lshlrev_b32_e32 v186, 3, v6
	v_lshlrev_b32_e32 v10, 2, v6
	v_lshl_add_u32 v190, v6, 4, v3
	v_lshrrev_b32_e32 v6, 2, v2
	v_and_b32_e32 v2, 16, v2
	v_lshlrev_b32_e32 v11, 2, v4
	s_movk_i32 s6, 0x140
	v_and_or_b32 v2, v11, 12, v2
	v_lshlrev_b32_e32 v183, 3, v8
	v_mad_u32_u24 v8, v7, s73, v3
	v_mad_u32_u24 v9, v7, s6, v3
	v_and_or_b32 v6, v6, 3, v10
	v_lshl_add_u32 v191, v2, 1, v3
	v_sub_u32_e32 v2, v10, v4
	v_mov_b32_e32 v50, v1
	v_mov_b32_e32 v51, v1
	v_mul_u32_u24_e32 v187, 0x110, v4
	v_mul_u32_u24_e32 v192, 0x140, v6
	v_add_u32_e32 v156, v7, v152
	v_sub_u32_e32 v174, v2, v5
	v_mov_b32_e32 v52, v1
	v_mov_b32_e32 v53, v1
	v_mov_b32_e32 v54, v1
	v_mov_b32_e32 v55, v1
	v_mov_b32_e32 v56, v1
	v_mov_b32_e32 v57, v1
	v_mov_b32_e32 v58, v1
	v_mov_b32_e32 v59, v1
	v_mov_b32_e32 v60, v1
	v_mov_b32_e32 v61, v1
	v_mov_b32_e32 v62, v1
	v_mov_b32_e32 v63, v1
	v_mov_b32_e32 v64, v1
	v_mov_b32_e32 v65, v1
	v_add_u32_e32 v195, v8, v150
	v_add_u32_e32 v196, v9, v150
	v_mov_b64_e32 v[34:35], v[50:51]
	v_mov_b64_e32 v[18:19], v[50:51]
	v_mov_b64_e32 v[2:3], v[50:51]
	v_lshlrev_b32_e32 v184, 7, v173
	v_subrev_u32_e32 v188, 64, v181
	v_add_u32_e32 v189, 0x5f, v181
	v_add_u32_e32 v158, 48, v156
	v_mov_b32_e32 v159, v1
	v_add_u32_e32 v160, 32, v156
	v_mov_b32_e32 v161, v1
	v_add_u32_e32 v162, 16, v156
	v_mov_b32_e32 v163, v1
	v_mov_b32_e32 v157, v1
	v_mov_b32_e32 v153, v1
	v_mov_b32_e32 v175, v1
	v_mov_b32_e32 v193, 0xf149f2ca
	v_mov_b32_e32 v194, 0
	s_mov_b64 s[6:7], 0
	v_mov_b64_e32 v[36:37], v[52:53]
	v_mov_b64_e32 v[38:39], v[54:55]
	v_mov_b64_e32 v[40:41], v[56:57]
	v_mov_b64_e32 v[42:43], v[58:59]
	v_mov_b64_e32 v[44:45], v[60:61]
	v_mov_b64_e32 v[46:47], v[62:63]
	v_mov_b64_e32 v[48:49], v[64:65]
	v_mov_b64_e32 v[20:21], v[52:53]
	v_mov_b64_e32 v[22:23], v[54:55]
	v_mov_b64_e32 v[24:25], v[56:57]
	v_mov_b64_e32 v[26:27], v[58:59]
	v_mov_b64_e32 v[28:29], v[60:61]
	v_mov_b64_e32 v[30:31], v[62:63]
	v_mov_b64_e32 v[32:33], v[64:65]
	v_mov_b64_e32 v[4:5], v[52:53]
	v_mov_b64_e32 v[6:7], v[54:55]
	v_mov_b64_e32 v[8:9], v[56:57]
	v_mov_b64_e32 v[10:11], v[58:59]
	v_mov_b64_e32 v[12:13], v[60:61]
	v_mov_b64_e32 v[14:15], v[62:63]
	v_mov_b64_e32 v[16:17], v[64:65]
	s_waitcnt vmcnt(0)
	ds_write_b32 v253, v252
	s_branch .LBB0_166

; #define LAS __attribute__((address_space(3)))
; #define D2_LOADK(tt) do { const unsigned char* zt_ = Zt + (size_t)(tt) * (64 * 1024 * 2); gk0 = *(const v4u*)(zt_ + oK); gk1 = *(const v4u*)(zt_ + oK + 1024); } while (0)
; #define D2_LOADV(tt) do { const unsigned char* zt_ = ZtV + (size_t)(tt) * (64 * 1024 * 2); gv0 = *(const v4u*)(zt_ + oV); gv1 = *(const v4u*)(zt_ + oV + 32 * 1024 * 2); } while (0)
; __device__ __forceinline__ void diff2_item(const Params& p, LAS unsigned char* lds, const int item, const float lam, const float lam_init) {
;     ...
;     for (int ks = 0; ks < 4; ++ks) Q[ks] = *(const v8s*)(Z + (size_t)T * OFF_DQ + tq * 1024 + mp * 512 + hh * 64 + ks * 16 + h * 8);
;     v16f O[4]; float m_ = NEGBIG, l_ = 0.f;
; #pragma unroll
;     for (int eb = 0; eb < 4; ++eb)
; #pragma unroll
;         for (int i = 0; i < 16; ++i) O[eb][i] = 0.f;
;     const int rowK = tid >> 3, cc = tid & 7, rowV = tid >> 4, ccV = tid & 15;
;     const unsigned char* Zt = (const unsigned char*)(Z + (size_t)T * OFF_DK + ((size_t)b * 2048) * 1024 + hh * 64);
;     const unsigned char* ZtV = (const unsigned char*)(Z + (size_t)T * OFF_DV + ((size_t)b * 2048) * 1024 + hh * 128);
;     const unsigned oK = (unsigned)(rowK * 1024 + cc * 8) * 2u;
;     const unsigned oV = (unsigned)(rowV * 1024 + ccV * 8) * 2u;
;     LAS unsigned char* dK = lds + rowK * 144 + cc * 16;
;     LAS unsigned char* dV = lds + D2_VR + rowV * 320 + ccV * 16;
;     ...
;     v4u gk0, gk1, gv0, gv1;
;     D2_LOADK(0);
;     *(LAS v4u*)dK = gk0; *(LAS v4u*)(dK + D2_K1) = gk1;
;     D2_LOADK(1); D2_LOADV(0);
;     __syncthreads();
;     const float c1 = 0.125f * LOG2E;
;     const LAS unsigned char* kb0 = lds + mp * D2_K1 + r * 144 + h * 16;
;     const int q_ = (lane >> 2) & 3, p_ = lane & 3, g1_ = (lane >> 4) & 1;
;     const LAS unsigned char* vb_lane = lds + D2_VR + ((4 * h + q_) * 320 + (16 * g1_ + 4 * p_) * 2);
.LBB0_323:
	s_or_b64 exec, exec, s[6:7]
	s_lshl_b32 s6, s20, 4
	v_readlane_b32 s7, v249, 42
	s_add_i32 s6, s6, s7
	v_bfe_u32 v175, v2, 6, 2
	s_ashr_i32 s6, s6, 3
	v_lshlrev_b32_e32 v3, 5, v175
	s_ashr_i32 s7, s6, 31
	v_or_b32_e32 v0, s52, v3
	s_lshl_b64 s[10:11], s[6:7], 11
	v_and_b32_e32 v174, 31, v2
	v_or_b32_e32 v149, s10, v0
	v_ashrrev_i32_e32 v178, 8, v2
	v_mov_b32_e32 v147, s11
	v_or_b32_e32 v146, v149, v174
	v_lshlrev_b64 v[4:5], 11, v[146:147]
	v_lshlrev_b32_e32 v6, 9, v178
	v_lshl_add_u64 v[4:5], s[46:47], 0, v[4:5]
	v_ashrrev_i32_e32 v7, 31, v6
	v_bfe_u32 v8, v2, 5, 1
	v_lshl_add_u64 v[4:5], v[6:7], 1, v[4:5]
	s_mov_b32 s31, s29
	v_lshl_add_u64 v[4:5], v[4:5], 0, s[30:31]
	v_lshlrev_b32_e32 v6, 4, v8
	v_mov_b32_e32 v7, v1
	v_lshl_add_u64 v[4:5], v[4:5], 0, v[6:7]
	s_lshl_b64 s[6:7], s[6:7], 22
	v_readlane_b32 s10, v249, 46
	v_lshlrev_b32_e32 v146, 4, v2
	global_load_dwordx4 v[98:101], v[4:5], off
	global_load_dwordx4 v[102:105], v[4:5], off offset:32
	global_load_dwordx4 v[106:109], v[4:5], off offset:64
	global_load_dwordx4 v[110:113], v[4:5], off offset:96
	v_ashrrev_i32_e32 v5, 3, v2
	s_add_u32 s10, s10, s6
	v_readlane_b32 s11, v249, 48
	v_and_b32_e32 v9, 0x70, v146
	s_addc_u32 s11, s11, s7
	v_lshl_or_b32 v0, v5, 11, v9
	s_nop 1
	global_load_dwordx4 v[10:13], v0, s[10:11]
	global_load_dwordx4 v[14:17], v0, s[10:11] offset:1024
	s_movk_i32 s21, 0x90
	v_mul_lo_u32 v5, v5, s21
	v_and_b32_e32 v4, 15, v2
	v_readlane_b32 s18, v249, 50
	v_add3_u32 v179, 0, v5, v9
	v_lshl_add_u64 v[18:19], s[10:11], 0, v[0:1]
	v_ashrrev_i32_e32 v7, 4, v2
	s_add_u32 s18, s18, s6
	v_readlane_b32 s19, v249, 52
	v_lshlrev_b32_e32 v148, 4, v4
	s_mov_b64 s[10:11], 0x20000
	s_addc_u32 s19, s19, s7
	v_lshl_or_b32 v4, v7, 11, v148
	v_mov_b32_e32 v5, v1
	v_lshl_add_u64 v[252:253], v[18:19], 0, s[10:11]
	v_lshl_add_u64 v[254:255], s[18:19], 0, v[4:5]
	s_nop 1
	global_load_dwordx4 v[114:117], v[252:253], off
	global_load_dwordx4 v[118:121], v[252:253], off offset:1024
	v_add_co_u32_e32 v254, vcc, 0x10000, v254
	global_load_dwordx4 v[122:125], v4, s[18:19]
	s_nop 0
	v_addc_co_u32_e32 v255, vcc, 0, v255, vcc
	global_load_dwordx4 v[126:129], v[254:255], off
	s_waitcnt vmcnt(5)
	ds_write_b128 v179, v[10:13]
	s_waitcnt vmcnt(4)
	ds_write_b128 v179, v[14:17] offset:9216
	s_movk_i32 s10, 0x100
	v_cmp_gt_u32_e64 s[36:37], s10, v2
	s_movk_i32 s10, 0xff
	v_cmp_lt_u32_e64 s[38:39], s10, v2
	s_waitcnt lgkmcnt(0)
	s_barrier
	s_and_saveexec_b64 s[10:11], s[38:39]
	s_xor_b64 s[10:11], exec, s[10:11]
	s_or_saveexec_b64 s[10:11], s[10:11]
	v_mad_i32_i24 v9, v178, s73, 0
	v_mul_u32_u24_e32 v10, 0x90, v174
	v_add3_u32 v181, v9, v10, v6
	s_xor_b64 exec, exec, s[10:11]
	s_cbranch_execz .LBB0_325
	ds_read_b128 v[10:13], v181
	ds_read_b128 v[14:17], v181 offset:32
	ds_read_b128 v[18:21], v181 offset:64
	ds_read_b128 v[22:25], v181 offset:96
	s_waitcnt lgkmcnt(3)
	v_mfma_f32_32x32x16_bf16 v[66:81], v[10:13], v[98:101], 0
	s_waitcnt lgkmcnt(2)
	v_mfma_f32_32x32x16_bf16 v[66:81], v[14:17], v[102:105], v[66:81]
	s_waitcnt lgkmcnt(1)
	v_mfma_f32_32x32x16_bf16 v[66:81], v[18:21], v[106:109], v[66:81]
	s_waitcnt lgkmcnt(0)
	v_mfma_f32_32x32x16_bf16 v[66:81], v[22:25], v[110:113], v[66:81]
	ds_read_b128 v[10:13], v181 offset:4608
	ds_read_b128 v[14:17], v181 offset:4640
	ds_read_b128 v[18:21], v181 offset:4672
	ds_read_b128 v[22:25], v181 offset:4704
	s_waitcnt lgkmcnt(3)
	v_mfma_f32_32x32x16_bf16 v[82:97], v[10:13], v[98:101], 0
	s_waitcnt lgkmcnt(2)
	v_mfma_f32_32x32x16_bf16 v[82:97], v[14:17], v[102:105], v[82:97]
	s_waitcnt lgkmcnt(1)
	v_mfma_f32_32x32x16_bf16 v[82:97], v[18:21], v[106:109], v[82:97]
	s_waitcnt lgkmcnt(0)
	v_mfma_f32_32x32x16_bf16 v[82:97], v[22:25], v[110:113], v[82:97]

; __global__ void __launch_bounds__(512, 2) mega_fwd(Params p) {
	.amdhsa_kernel _Z8mega_fwd6Params
		.amdhsa_group_segment_fixed_size 0
		.amdhsa_private_segment_fixed_size 0
		.amdhsa_kernarg_size 376
		.amdhsa_user_sgpr_count 2
		.amdhsa_user_sgpr_dispatch_ptr 0
		.amdhsa_user_sgpr_queue_ptr 0
		.amdhsa_user_sgpr_kernarg_segment_ptr 1
		.amdhsa_user_sgpr_dispatch_id 0
		.amdhsa_user_sgpr_kernarg_preload_length 0
		.amdhsa_user_sgpr_kernarg_preload_offset 0
		.amdhsa_user_sgpr_private_segment_size 0
		.amdhsa_uses_dynamic_stack 0
		.amdhsa_enable_private_segment 0
		.amdhsa_system_sgpr_workgroup_id_x 1
		.amdhsa_system_sgpr_workgroup_id_y 0
		.amdhsa_system_sgpr_workgroup_id_z 0
		.amdhsa_system_sgpr_workgroup_info 0
		.amdhsa_system_vgpr_workitem_id 2
		.amdhsa_next_free_vgpr 256
		.amdhsa_next_free_sgpr 102
		.amdhsa_accum_offset 256
		.amdhsa_reserve_vcc 1
		.amdhsa_float_round_mode_32 0
		.amdhsa_float_round_mode_16_64 0
		.amdhsa_float_denorm_mode_32 3
		.amdhsa_float_denorm_mode_16_64 3
		.amdhsa_dx10_clamp 1
		.amdhsa_ieee_mode 1
		.amdhsa_fp16_overflow 0
		.amdhsa_tg_split 0
		.amdhsa_exception_fp_ieee_invalid_op 0
		.amdhsa_exception_fp_denorm_src 0
		.amdhsa_exception_fp_ieee_div_zero 0
		.amdhsa_exception_fp_ieee_overflow 0
		.amdhsa_exception_fp_ieee_underflow 0
		.amdhsa_exception_fp_ieee_inexact 0
		.amdhsa_exception_int_div_zero 0
	.end_amdhsa_kernel

; __global__ void __launch_bounds__(512, 2) mega_fwd(Params p) {
amdhsa.kernels:
  - .agpr_count:     0
    .args:
      - .offset:         0
        .size:           120
        .value_kind:     by_value
      - .offset:         120
        .size:           4
        .value_kind:     hidden_block_count_x
      - .offset:         124
        .size:           4
        .value_kind:     hidden_block_count_y
      - .offset:         128
        .size:           4
        .value_kind:     hidden_block_count_z
      - .offset:         132
        .size:           2
        .value_kind:     hidden_group_size_x
      - .offset:         134
        .size:           2
        .value_kind:     hidden_group_size_y
      - .offset:         136
        .size:           2
        .value_kind:     hidden_group_size_z
      - .offset:         138
        .size:           2
        .value_kind:     hidden_remainder_x
      - .offset:         140
        .size:           2
        .value_kind:     hidden_remainder_y
      - .offset:         142
        .size:           2
        .value_kind:     hidden_remainder_z
      - .offset:         160
        .size:           8
        .value_kind:     hidden_global_offset_x
      - .offset:         168
        .size:           8
        .value_kind:     hidden_global_offset_y
      - .offset:         176
        .size:           8
        .value_kind:     hidden_global_offset_z
      - .offset:         184
        .size:           2
        .value_kind:     hidden_grid_dims
      - .offset:         208
        .size:           8
        .value_kind:     hidden_multigrid_sync_arg
      - .offset:         240
        .size:           4
        .value_kind:     hidden_dynamic_lds_size
    .group_segment_fixed_size: 0
    .kernarg_segment_align: 8
    .kernarg_segment_size: 376
    .language:       OpenCL C
    .language_version:
      - 2
      - 0
    .max_flat_workgroup_size: 512
    .name:           _Z8mega_fwd6Params
    .private_segment_fixed_size: 0
    .sgpr_count:     108
    .sgpr_spill_count: 223
    .symbol:         _Z8mega_fwd6Params.kd
    .uniform_work_group_size: 1
    .uses_dynamic_stack: false
    .vgpr_count:     256
    .vgpr_spill_count: 0
    .wavefront_size: 64
